# in_odd GEMM epilogue rewritten by hand (gelu as x*rcp(1+exp2(x*(c1+c2*x*x))) with packed f32, same f32 precision)
# speedup vs baseline: 1.0657x; 1.0056x over previous
.LBB0_123:
	s_add_u32 s2, s20, 0xfffc0080
	s_addc_u32 s3, s21, -1
	s_add_i32 s53, 0, 0x10000
	v_add_u32_e32 v36, s53, v164
	ds_read_b128 v[24:27], v36
	ds_read_b128 v[28:31], v36 offset:1024
	ds_read_b128 v[32:35], v36 offset:2048
	ds_read_b128 v[36:39], v36 offset:3072
	s_cmp_eq_u32 s52, 12
	s_cselect_b32 s23, s7, s3
	s_cselect_b32 s22, s9, s2
	s_cselect_b32 s3, s13, s51
	s_cselect_b32 s2, s15, s50
	v_lshl_add_u64 v[166:167], s[20:21], 0, v[150:151]
	s_add_i32 m0, s37, 0xc000
	ds_read_b128 v[154:157], v165
	ds_read_b128 v[158:161], v165 offset:1024
	ds_read_b128 v[180:183], v165 offset:2048
	ds_read_b128 v[184:187], v165 offset:3072
	ds_read_b128 v[188:191], v165 offset:4096
	ds_read_b128 v[192:195], v165 offset:5120
	ds_read_b128 v[196:199], v165 offset:6144
	ds_read_b128 v[200:203], v165 offset:7168
	global_load_lds_dwordx4 v[166:167], off
	v_lshl_add_u64 v[166:167], s[20:21], 0, v[152:153]
	s_add_i32 m0, s37, 0xe000
	s_nop 0
	global_load_lds_dwordx4 v[166:167], off
	s_waitcnt lgkmcnt(8)
	s_barrier
	s_waitcnt lgkmcnt(0)
	s_setprio 1
	s_waitcnt lgkmcnt(0)
	v_mfma_f32_16x16x32_bf16 v[140:143], v[24:27], v[154:157], v[140:143]
	v_mfma_f32_16x16x32_bf16 v[136:139], v[32:35], v[154:157], v[136:139]
	v_mfma_f32_16x16x32_bf16 v[124:127], v[24:27], v[180:183], v[124:127]
	v_mfma_f32_16x16x32_bf16 v[120:123], v[32:35], v[180:183], v[120:123]
	v_mfma_f32_16x16x32_bf16 v[108:111], v[24:27], v[188:191], v[108:111]
	v_mfma_f32_16x16x32_bf16 v[104:107], v[32:35], v[188:191], v[104:107]
	v_mfma_f32_16x16x32_bf16 v[92:95], v[24:27], v[196:199], v[92:95]
	v_mfma_f32_16x16x32_bf16 v[88:91], v[32:35], v[196:199], v[88:91]
	v_mfma_f32_16x16x32_bf16 v[140:143], v[28:31], v[158:161], v[140:143]
	v_mfma_f32_16x16x32_bf16 v[136:139], v[36:39], v[158:161], v[136:139]
	v_mfma_f32_16x16x32_bf16 v[124:127], v[28:31], v[184:187], v[124:127]
	v_mfma_f32_16x16x32_bf16 v[120:123], v[36:39], v[184:187], v[120:123]
	v_mfma_f32_16x16x32_bf16 v[108:111], v[28:31], v[192:195], v[108:111]
	v_mfma_f32_16x16x32_bf16 v[104:107], v[36:39], v[192:195], v[104:107]
	v_mfma_f32_16x16x32_bf16 v[92:95], v[28:31], v[200:203], v[92:95]
	v_mfma_f32_16x16x32_bf16 v[88:91], v[36:39], v[200:203], v[88:91]
	s_setprio 0
	s_barrier
	s_add_i32 s56, 0, 0x14000
	v_add_u32_e32 v166, s56, v164
	s_add_i32 s53, s53, s36
	ds_read_b128 v[204:207], v166
	ds_read_b128 v[208:211], v166 offset:1024
	ds_read_b128 v[212:215], v166 offset:2048
	ds_read_b128 v[216:219], v166 offset:3072
	v_lshl_add_u64 v[166:167], s[2:3], 0, v[168:169]
	s_mov_b32 m0, s53
	v_lshl_add_u64 v[220:221], s[2:3], 0, v[148:149]
	global_load_lds_dwordx4 v[166:167], off
	s_add_i32 m0, s53, 0x2000
	s_nop 0
	global_load_lds_dwordx4 v[220:221], off
	s_barrier
	s_waitcnt lgkmcnt(0)
	s_setprio 1
	s_waitcnt lgkmcnt(0)
	v_mfma_f32_16x16x32_bf16 v[132:135], v[204:207], v[154:157], v[132:135]
	v_mfma_f32_16x16x32_bf16 v[128:131], v[212:215], v[154:157], v[128:131]
	v_mfma_f32_16x16x32_bf16 v[116:119], v[204:207], v[180:183], v[116:119]
	v_mfma_f32_16x16x32_bf16 v[112:115], v[212:215], v[180:183], v[112:115]
	v_mfma_f32_16x16x32_bf16 v[100:103], v[204:207], v[188:191], v[100:103]
	v_mfma_f32_16x16x32_bf16 v[96:99], v[212:215], v[188:191], v[96:99]
	v_mfma_f32_16x16x32_bf16 v[84:87], v[204:207], v[196:199], v[84:87]
	v_mfma_f32_16x16x32_bf16 v[80:83], v[212:215], v[196:199], v[80:83]
	v_mfma_f32_16x16x32_bf16 v[132:135], v[208:211], v[158:161], v[132:135]
	v_mfma_f32_16x16x32_bf16 v[128:131], v[216:219], v[158:161], v[128:131]
	v_mfma_f32_16x16x32_bf16 v[116:119], v[208:211], v[184:187], v[116:119]
	v_mfma_f32_16x16x32_bf16 v[112:115], v[216:219], v[184:187], v[112:115]
	v_mfma_f32_16x16x32_bf16 v[100:103], v[208:211], v[192:195], v[100:103]
	v_mfma_f32_16x16x32_bf16 v[96:99], v[216:219], v[192:195], v[96:99]
	v_mfma_f32_16x16x32_bf16 v[84:87], v[208:211], v[200:203], v[84:87]
	v_mfma_f32_16x16x32_bf16 v[80:83], v[216:219], v[200:203], v[80:83]
	s_setprio 0
	s_mov_b32 m0, s37
	v_lshl_add_u64 v[222:223], s[22:23], 0, v[144:145]
	s_barrier
	ds_read_b128 v[154:157], v165 offset:16384
	ds_read_b128 v[158:161], v165 offset:17408
	ds_read_b128 v[180:183], v165 offset:18432
	ds_read_b128 v[184:187], v165 offset:19456
	ds_read_b128 v[188:191], v165 offset:20480
	ds_read_b128 v[192:195], v165 offset:21504
	ds_read_b128 v[196:199], v165 offset:22528
	ds_read_b128 v[200:203], v165 offset:23552
	global_load_lds_dwordx4 v[222:223], off
	v_lshl_add_u64 v[236:237], s[22:23], 0, v[146:147]
	s_mov_b32 m0, s38
	s_nop 0
	global_load_lds_dwordx4 v[236:237], off
	s_barrier
	s_waitcnt lgkmcnt(0)
	s_setprio 1
	s_waitcnt lgkmcnt(0)
	v_mfma_f32_16x16x32_bf16 v[76:79], v[24:27], v[154:157], v[76:79]
	v_mfma_f32_16x16x32_bf16 v[72:75], v[32:35], v[154:157], v[72:75]
	v_mfma_f32_16x16x32_bf16 v[60:63], v[24:27], v[180:183], v[60:63]
	v_mfma_f32_16x16x32_bf16 v[56:59], v[32:35], v[180:183], v[56:59]
	v_mfma_f32_16x16x32_bf16 v[44:47], v[24:27], v[188:191], v[44:47]
	v_mfma_f32_16x16x32_bf16 v[40:43], v[32:35], v[188:191], v[40:43]
	v_mfma_f32_16x16x32_bf16 v[12:15], v[24:27], v[196:199], v[12:15]
	v_mfma_f32_16x16x32_bf16 v[8:11], v[32:35], v[196:199], v[8:11]
	v_mfma_f32_16x16x32_bf16 v[76:79], v[28:31], v[158:161], v[76:79]
	v_mfma_f32_16x16x32_bf16 v[72:75], v[36:39], v[158:161], v[72:75]
	v_mfma_f32_16x16x32_bf16 v[60:63], v[28:31], v[184:187], v[60:63]
	v_mfma_f32_16x16x32_bf16 v[56:59], v[36:39], v[184:187], v[56:59]
	v_mfma_f32_16x16x32_bf16 v[44:47], v[28:31], v[192:195], v[44:47]
	v_mfma_f32_16x16x32_bf16 v[40:43], v[36:39], v[192:195], v[40:43]
	v_mfma_f32_16x16x32_bf16 v[12:15], v[28:31], v[200:203], v[12:15]
	v_mfma_f32_16x16x32_bf16 v[8:11], v[36:39], v[200:203], v[8:11]
	s_setprio 0
	s_barrier
	s_add_u32 s54, s2, 0x40000
	s_addc_u32 s55, s3, 0
	s_add_i32 s53, s56, s36
	v_lshl_add_u64 v[24:25], s[54:55], 0, v[168:169]
	s_mov_b32 m0, s53
	s_nop 0
	global_load_lds_dwordx4 v[24:25], off
	v_lshl_add_u64 v[24:25], s[54:55], 0, v[148:149]
	s_add_i32 m0, s53, 0x2000
	s_nop 0
	global_load_lds_dwordx4 v[24:25], off
	s_waitcnt vmcnt(6)
	s_barrier
	s_setprio 1
	v_mfma_f32_16x16x32_bf16 v[20:23], v[204:207], v[188:191], v[20:23]
	v_mfma_f32_16x16x32_bf16 v[16:19], v[212:215], v[188:191], v[16:19]
	v_mfma_f32_16x16x32_bf16 v[4:7], v[204:207], v[196:199], v[4:7]
	v_mfma_f32_16x16x32_bf16 v[0:3], v[212:215], v[196:199], v[0:3]
	v_mfma_f32_16x16x32_bf16 v[24:27], v[204:207], v[154:157], v[68:71]
	v_mfma_f32_16x16x32_bf16 v[28:31], v[212:215], v[154:157], v[64:67]
	v_mfma_f32_16x16x32_bf16 v[32:35], v[204:207], v[180:183], v[52:55]
	v_mfma_f32_16x16x32_bf16 v[36:39], v[212:215], v[180:183], v[48:51]
	v_mfma_f32_16x16x32_bf16 v[20:23], v[208:211], v[192:195], v[20:23]
	v_mfma_f32_16x16x32_bf16 v[16:19], v[216:219], v[192:195], v[16:19]
	v_mfma_f32_16x16x32_bf16 v[4:7], v[208:211], v[200:203], v[4:7]
	v_mfma_f32_16x16x32_bf16 v[0:3], v[216:219], v[200:203], v[0:3]
	v_mfma_f32_16x16x32_bf16 v[24:27], v[208:211], v[158:161], v[24:27]
	v_mfma_f32_16x16x32_bf16 v[28:31], v[216:219], v[158:161], v[28:31]
	v_mfma_f32_16x16x32_bf16 v[32:35], v[208:211], v[184:187], v[32:35]
	v_mfma_f32_16x16x32_bf16 v[36:39], v[216:219], v[184:187], v[36:39]
	s_setprio 0
	s_add_i32 s53, 0, 0x18000
	v_add_u32_e32 v68, s53, v164
	s_barrier
	ds_read_b128 v[48:51], v68
	ds_read_b128 v[52:55], v68 offset:1024
	ds_read_b128 v[64:67], v68 offset:2048
	ds_read_b128 v[68:71], v68 offset:3072
	s_add_u32 s22, s22, 0x40000
	s_addc_u32 s23, s23, 0
	s_mov_b32 m0, s39
	v_lshl_add_u64 v[204:205], s[22:23], 0, v[144:145]
	ds_read_b128 v[154:157], v165 offset:32768
	ds_read_b128 v[158:161], v165 offset:33792
	ds_read_b128 v[180:183], v165 offset:34816
	ds_read_b128 v[184:187], v165 offset:35840
	ds_read_b128 v[188:191], v165 offset:36864
	ds_read_b128 v[192:195], v165 offset:37888
	ds_read_b128 v[196:199], v165 offset:38912
	ds_read_b128 v[200:203], v165 offset:39936
	global_load_lds_dwordx4 v[204:205], off
	v_lshl_add_u64 v[204:205], s[22:23], 0, v[146:147]
	s_mov_b32 m0, s40
	s_nop 0
	global_load_lds_dwordx4 v[204:205], off
	s_waitcnt lgkmcnt(8)
	s_barrier
	s_waitcnt lgkmcnt(0)
	s_setprio 1
	s_waitcnt lgkmcnt(0)
	v_mfma_f32_16x16x32_bf16 v[140:143], v[48:51], v[154:157], v[140:143]
	v_mfma_f32_16x16x32_bf16 v[136:139], v[64:67], v[154:157], v[136:139]
	v_mfma_f32_16x16x32_bf16 v[124:127], v[48:51], v[180:183], v[124:127]
	v_mfma_f32_16x16x32_bf16 v[120:123], v[64:67], v[180:183], v[120:123]
	v_mfma_f32_16x16x32_bf16 v[108:111], v[48:51], v[188:191], v[108:111]
	v_mfma_f32_16x16x32_bf16 v[104:107], v[64:67], v[188:191], v[104:107]
	v_mfma_f32_16x16x32_bf16 v[92:95], v[48:51], v[196:199], v[92:95]
	v_mfma_f32_16x16x32_bf16 v[88:91], v[64:67], v[196:199], v[88:91]
	v_mfma_f32_16x16x32_bf16 v[140:143], v[52:55], v[158:161], v[140:143]
	v_mfma_f32_16x16x32_bf16 v[136:139], v[68:71], v[158:161], v[136:139]
	v_mfma_f32_16x16x32_bf16 v[124:127], v[52:55], v[184:187], v[124:127]
	v_mfma_f32_16x16x32_bf16 v[120:123], v[68:71], v[184:187], v[120:123]
	v_mfma_f32_16x16x32_bf16 v[108:111], v[52:55], v[192:195], v[108:111]
	v_mfma_f32_16x16x32_bf16 v[104:107], v[68:71], v[192:195], v[104:107]
	v_mfma_f32_16x16x32_bf16 v[92:95], v[52:55], v[200:203], v[92:95]
	v_mfma_f32_16x16x32_bf16 v[88:91], v[68:71], v[200:203], v[88:91]
	s_setprio 0
	s_barrier
	s_add_i32 s22, 0, 0x1c000
	s_add_i32 s23, s53, s36
	v_add_u32_e32 v216, s22, v164
	v_lshl_add_u64 v[166:167], v[166:167], 0, s[78:79]
	s_mov_b32 m0, s23
	ds_read_b128 v[204:207], v216
	ds_read_b128 v[208:211], v216 offset:1024
	ds_read_b128 v[212:215], v216 offset:2048
	ds_read_b128 v[216:219], v216 offset:3072
	global_load_lds_dwordx4 v[166:167], off
	v_lshl_add_u64 v[166:167], v[220:221], 0, s[78:79]
	s_add_i32 m0, s23, 0x2000
	s_nop 0
	global_load_lds_dwordx4 v[166:167], off
	s_barrier
	s_waitcnt lgkmcnt(0)
	s_setprio 1
	s_waitcnt lgkmcnt(0)
	v_mfma_f32_16x16x32_bf16 v[132:135], v[204:207], v[154:157], v[132:135]
	v_mfma_f32_16x16x32_bf16 v[128:131], v[212:215], v[154:157], v[128:131]
	v_mfma_f32_16x16x32_bf16 v[116:119], v[204:207], v[180:183], v[116:119]
	v_mfma_f32_16x16x32_bf16 v[112:115], v[212:215], v[180:183], v[112:115]
	v_mfma_f32_16x16x32_bf16 v[100:103], v[204:207], v[188:191], v[100:103]
	v_mfma_f32_16x16x32_bf16 v[96:99], v[212:215], v[188:191], v[96:99]
	v_mfma_f32_16x16x32_bf16 v[84:87], v[204:207], v[196:199], v[84:87]
	v_mfma_f32_16x16x32_bf16 v[80:83], v[212:215], v[196:199], v[80:83]
	v_mfma_f32_16x16x32_bf16 v[132:135], v[208:211], v[158:161], v[132:135]
	v_mfma_f32_16x16x32_bf16 v[128:131], v[216:219], v[158:161], v[128:131]
	v_mfma_f32_16x16x32_bf16 v[116:119], v[208:211], v[184:187], v[116:119]
	v_mfma_f32_16x16x32_bf16 v[112:115], v[216:219], v[184:187], v[112:115]
	v_mfma_f32_16x16x32_bf16 v[100:103], v[208:211], v[192:195], v[100:103]
	v_mfma_f32_16x16x32_bf16 v[96:99], v[216:219], v[192:195], v[96:99]
	v_mfma_f32_16x16x32_bf16 v[84:87], v[208:211], v[200:203], v[84:87]
	v_mfma_f32_16x16x32_bf16 v[80:83], v[216:219], v[200:203], v[80:83]
	s_setprio 0
	s_mov_b32 m0, s45
	v_lshl_add_u64 v[166:167], v[222:223], 0, s[78:79]
	s_barrier
	ds_read_b128 v[154:157], v165 offset:49152
	ds_read_b128 v[158:161], v165 offset:50176
	ds_read_b128 v[180:183], v165 offset:51200
	ds_read_b128 v[184:187], v165 offset:52224
	ds_read_b128 v[188:191], v165 offset:53248
	ds_read_b128 v[192:195], v165 offset:54272
	ds_read_b128 v[196:199], v165 offset:55296
	ds_read_b128 v[200:203], v165 offset:56320
	global_load_lds_dwordx4 v[166:167], off
	v_lshl_add_u64 v[166:167], v[236:237], 0, s[78:79]
	s_mov_b32 m0, s46
	s_nop 0
	global_load_lds_dwordx4 v[166:167], off
	s_barrier
	s_waitcnt lgkmcnt(0)
	s_setprio 1
	s_waitcnt lgkmcnt(0)
	v_mfma_f32_16x16x32_bf16 v[76:79], v[48:51], v[154:157], v[76:79]
	v_mfma_f32_16x16x32_bf16 v[72:75], v[64:67], v[154:157], v[72:75]
	v_mfma_f32_16x16x32_bf16 v[60:63], v[48:51], v[180:183], v[60:63]
	v_mfma_f32_16x16x32_bf16 v[56:59], v[64:67], v[180:183], v[56:59]
	v_mfma_f32_16x16x32_bf16 v[44:47], v[48:51], v[188:191], v[44:47]
	v_mfma_f32_16x16x32_bf16 v[40:43], v[64:67], v[188:191], v[40:43]
	v_mfma_f32_16x16x32_bf16 v[12:15], v[48:51], v[196:199], v[12:15]
	v_mfma_f32_16x16x32_bf16 v[8:11], v[64:67], v[196:199], v[8:11]
	v_mfma_f32_16x16x32_bf16 v[76:79], v[52:55], v[158:161], v[76:79]
	v_mfma_f32_16x16x32_bf16 v[72:75], v[68:71], v[158:161], v[72:75]
	v_mfma_f32_16x16x32_bf16 v[60:63], v[52:55], v[184:187], v[60:63]
	v_mfma_f32_16x16x32_bf16 v[56:59], v[68:71], v[184:187], v[56:59]
	v_mfma_f32_16x16x32_bf16 v[44:47], v[52:55], v[192:195], v[44:47]
	v_mfma_f32_16x16x32_bf16 v[40:43], v[68:71], v[192:195], v[40:43]
	v_mfma_f32_16x16x32_bf16 v[12:15], v[52:55], v[200:203], v[12:15]
	v_mfma_f32_16x16x32_bf16 v[8:11], v[68:71], v[200:203], v[8:11]
	s_setprio 0
	s_barrier
	s_add_u32 s2, s2, 0x40080
	s_addc_u32 s3, s3, 0
	s_add_i32 s22, s22, s36
	v_lshl_add_u64 v[48:49], s[2:3], 0, v[168:169]
	s_mov_b32 m0, s22
	s_nop 0
	global_load_lds_dwordx4 v[48:49], off
	v_lshl_add_u64 v[48:49], s[2:3], 0, v[148:149]
	s_add_i32 m0, s22, 0x2000
	s_nop 0
	global_load_lds_dwordx4 v[48:49], off
	s_waitcnt vmcnt(6)
	s_barrier
	s_setprio 1
	v_mfma_f32_16x16x32_bf16 v[24:27], v[204:207], v[154:157], v[24:27]
	v_mfma_f32_16x16x32_bf16 v[68:71], v[208:211], v[158:161], v[24:27]
	v_mfma_f32_16x16x32_bf16 v[24:27], v[212:215], v[154:157], v[28:31]
	v_mfma_f32_16x16x32_bf16 v[64:67], v[216:219], v[158:161], v[24:27]
	v_mfma_f32_16x16x32_bf16 v[24:27], v[204:207], v[180:183], v[32:35]
	v_mfma_f32_16x16x32_bf16 v[52:55], v[208:211], v[184:187], v[24:27]
	v_mfma_f32_16x16x32_bf16 v[24:27], v[212:215], v[180:183], v[36:39]
	v_mfma_f32_16x16x32_bf16 v[20:23], v[204:207], v[188:191], v[20:23]
	v_mfma_f32_16x16x32_bf16 v[16:19], v[212:215], v[188:191], v[16:19]
	v_mfma_f32_16x16x32_bf16 v[4:7], v[204:207], v[196:199], v[4:7]
	v_mfma_f32_16x16x32_bf16 v[0:3], v[212:215], v[196:199], v[0:3]
	v_mfma_f32_16x16x32_bf16 v[48:51], v[216:219], v[184:187], v[24:27]
	v_mfma_f32_16x16x32_bf16 v[20:23], v[208:211], v[192:195], v[20:23]
	v_mfma_f32_16x16x32_bf16 v[16:19], v[216:219], v[192:195], v[16:19]
	v_mfma_f32_16x16x32_bf16 v[4:7], v[208:211], v[200:203], v[4:7]
	v_mfma_f32_16x16x32_bf16 v[0:3], v[216:219], v[200:203], v[0:3]
	s_setprio 0
	s_add_i32 s52, s52, 2
	s_add_u32 s20, s20, 0x100
	s_addc_u32 s21, s21, 0
	s_add_u32 s50, s50, 0x100
	s_addc_u32 s51, s51, 0
	s_cmp_gt_u32 s52, 13
	s_barrier
	s_cbranch_scc0 .LBB0_123
	s_lshl_b32 s2, s6, 8
	s_add_i32 s3, s2, s43
	s_lshl_b32 s2, s8, 8
	s_cmp_gt_i32 s8, 3
	s_cselect_b64 s[20:21], -1, 0
	s_and_b64 s[22:23], s[20:21], exec
	s_mov_b32 s7, 0x8982000
	s_cselect_b32 s7, s7, 0x7182000
	s_add_u32 s22, s26, s7
	s_addc_u32 s23, s25, 0
	s_add_i32 s7, s6, -16
	v_mov_b32_e32 v160, v163
	v_mov_b32_e32 v24, v162
	s_lshr_b32 s7, s7, 3
	s_add_i32 s96, s7, 1
	v_add_u32_e32 v154, s3, v24
	s_lshl_b64 s[50:51], s[96:97], 11
	v_ashrrev_i32_e32 v155, 31, v154
	s_cmp_gt_i32 s6, 15
	v_lshl_add_u64 v[156:157], v[154:155], 2, s[10:11]
	s_cselect_b32 s7, s51, 0
	s_cselect_b32 s6, s50, 0
	global_load_dword v166, v[156:157], off
	global_load_dword v191, v[156:157], off offset:64
	global_load_dword v192, v[156:157], off offset:128
	global_load_dword v193, v[156:157], off offset:192
	global_load_dword v194, v[156:157], off offset:512
	global_load_dword v195, v[156:157], off offset:576
	global_load_dword v196, v[156:157], off offset:640
	global_load_dword v197, v[156:157], off offset:704
	s_lshl_b64 s[6:7], s[6:7], 2
	s_add_u32 s9, s41, s6
	s_addc_u32 s13, s42, s7
	s_ashr_i32 s3, s2, 31
	s_lshl_b64 s[6:7], s[2:3], 2
	s_add_u32 s3, s9, s6
	s_addc_u32 s7, s13, s7
	v_lshlrev_b32_e32 v158, 3, v160
	s_add_u32 s6, s3, s49
	s_addc_u32 s7, s7, 0
	v_ashrrev_i32_e32 v159, 31, v158
	v_lshl_add_u64 v[24:25], v[158:159], 2, s[6:7]
	global_load_dwordx4 v[36:39], v[24:25], off
	global_load_dwordx4 v[32:35], v[24:25], off offset:16
	global_load_dwordx4 v[28:31], v[24:25], off offset:512
	s_nop 0
	global_load_dwordx4 v[24:27], v[24:25], off offset:528
	s_and_b32 s2, s2, 0x300
	s_or_b32 s2, s2, s44
	v_add_u32_e32 v158, s2, v158
	v_cmp_eq_u32_e64 s[6:7], 0, v160
	v_lshlrev_b64 v[160:161], 11, v[154:155]
	s_cmp_lt_i32 s8, 4
	s_waitcnt vmcnt(0)
	v_ashrrev_i32_e32 v159, 31, v158
	v_lshl_add_u64 v[158:159], v[158:159], 1, s[22:23]
	v_lshl_add_u64 v[160:161], v[158:159], 0, v[160:161]
	v_lshl_add_u64 v[156:157], v[154:155], 2, s[0:1]
	s_and_b64 s[6:7], s[6:7], s[20:21]
	s_mov_b64 s[2:3], 0x8000
	s_mov_b64 s[50:51], 0x28000
	v_mov_b32_e32 v180, 0xc0135761
	v_mov_b32_e32 v181, 0xc0135761
	v_mov_b32_e32 v182, 0xbdd2d3e7
	v_mov_b32_e32 v183, 0xbdd2d3e7
	v_fmamk_f32 v166, v166, 0x3a800000, v225
	v_fmamk_f32 v190, v191, 0x3a800000, v225
	v_fmamk_f32 v192, v192, 0x3a800000, v225
	v_fmamk_f32 v188, v193, 0x3a800000, v225
	v_fmamk_f32 v194, v194, 0x3a800000, v225
	v_fmamk_f32 v186, v195, 0x3a800000, v225
	v_fmamk_f32 v196, v196, 0x3a800000, v225
	v_fmamk_f32 v184, v197, 0x3a800000, v225
	v_rsq_f32_e32 v166, v166
	v_rsq_f32_e32 v190, v190
	v_rsq_f32_e32 v192, v192
	v_rsq_f32_e32 v188, v188
	v_rsq_f32_e32 v194, v194
	v_rsq_f32_e32 v186, v186
	v_rsq_f32_e32 v196, v196
	v_rsq_f32_e32 v184, v184
	v_pk_fma_f32 v[140:141], v[140:141], v[166:167], v[36:37] op_sel_hi:[1,0,1]
	v_pk_fma_f32 v[142:143], v[142:143], v[166:167], v[38:39] op_sel_hi:[1,0,1]
	v_pk_fma_f32 v[136:137], v[136:137], v[166:167], v[32:33] op_sel_hi:[1,0,1]
	v_pk_fma_f32 v[138:139], v[138:139], v[166:167], v[34:35] op_sel_hi:[1,0,1]
	v_pk_fma_f32 v[132:133], v[132:133], v[166:167], v[28:29] op_sel_hi:[1,0,1]
	v_pk_fma_f32 v[134:135], v[134:135], v[166:167], v[30:31] op_sel_hi:[1,0,1]
	v_pk_fma_f32 v[128:129], v[128:129], v[166:167], v[24:25] op_sel_hi:[1,0,1]
	v_pk_fma_f32 v[130:131], v[130:131], v[166:167], v[26:27] op_sel_hi:[1,0,1]
	v_pk_fma_f32 v[124:125], v[124:125], v[190:191], v[36:37] op_sel_hi:[1,0,1]
	v_pk_fma_f32 v[126:127], v[126:127], v[190:191], v[38:39] op_sel_hi:[1,0,1]
	v_pk_fma_f32 v[120:121], v[120:121], v[190:191], v[32:33] op_sel_hi:[1,0,1]
	v_pk_fma_f32 v[122:123], v[122:123], v[190:191], v[34:35] op_sel_hi:[1,0,1]
	v_pk_fma_f32 v[116:117], v[116:117], v[190:191], v[28:29] op_sel_hi:[1,0,1]
	v_pk_fma_f32 v[118:119], v[118:119], v[190:191], v[30:31] op_sel_hi:[1,0,1]
	v_pk_fma_f32 v[112:113], v[112:113], v[190:191], v[24:25] op_sel_hi:[1,0,1]
	v_pk_fma_f32 v[114:115], v[114:115], v[190:191], v[26:27] op_sel_hi:[1,0,1]
	v_pk_fma_f32 v[108:109], v[108:109], v[192:193], v[36:37] op_sel_hi:[1,0,1]
	v_pk_fma_f32 v[110:111], v[110:111], v[192:193], v[38:39] op_sel_hi:[1,0,1]
	v_pk_fma_f32 v[104:105], v[104:105], v[192:193], v[32:33] op_sel_hi:[1,0,1]
	v_pk_fma_f32 v[106:107], v[106:107], v[192:193], v[34:35] op_sel_hi:[1,0,1]
	v_pk_fma_f32 v[100:101], v[100:101], v[192:193], v[28:29] op_sel_hi:[1,0,1]
	v_pk_fma_f32 v[102:103], v[102:103], v[192:193], v[30:31] op_sel_hi:[1,0,1]
	v_pk_fma_f32 v[96:97], v[96:97], v[192:193], v[24:25] op_sel_hi:[1,0,1]
	v_pk_fma_f32 v[98:99], v[98:99], v[192:193], v[26:27] op_sel_hi:[1,0,1]
	v_pk_fma_f32 v[92:93], v[92:93], v[188:189], v[36:37] op_sel_hi:[1,0,1]
	v_pk_fma_f32 v[94:95], v[94:95], v[188:189], v[38:39] op_sel_hi:[1,0,1]
	v_pk_fma_f32 v[88:89], v[88:89], v[188:189], v[32:33] op_sel_hi:[1,0,1]
	v_pk_fma_f32 v[90:91], v[90:91], v[188:189], v[34:35] op_sel_hi:[1,0,1]
	v_pk_fma_f32 v[84:85], v[84:85], v[188:189], v[28:29] op_sel_hi:[1,0,1]
	v_pk_fma_f32 v[86:87], v[86:87], v[188:189], v[30:31] op_sel_hi:[1,0,1]
	v_pk_fma_f32 v[80:81], v[80:81], v[188:189], v[24:25] op_sel_hi:[1,0,1]
	v_pk_fma_f32 v[82:83], v[82:83], v[188:189], v[26:27] op_sel_hi:[1,0,1]
	v_pk_fma_f32 v[76:77], v[76:77], v[194:195], v[36:37] op_sel_hi:[1,0,1]
	v_pk_fma_f32 v[78:79], v[78:79], v[194:195], v[38:39] op_sel_hi:[1,0,1]
	v_pk_fma_f32 v[72:73], v[72:73], v[194:195], v[32:33] op_sel_hi:[1,0,1]
	v_pk_fma_f32 v[74:75], v[74:75], v[194:195], v[34:35] op_sel_hi:[1,0,1]
	v_pk_fma_f32 v[68:69], v[68:69], v[194:195], v[28:29] op_sel_hi:[1,0,1]
	v_pk_fma_f32 v[70:71], v[70:71], v[194:195], v[30:31] op_sel_hi:[1,0,1]
	v_pk_fma_f32 v[64:65], v[64:65], v[194:195], v[24:25] op_sel_hi:[1,0,1]
	v_pk_fma_f32 v[66:67], v[66:67], v[194:195], v[26:27] op_sel_hi:[1,0,1]
	v_pk_fma_f32 v[60:61], v[60:61], v[186:187], v[36:37] op_sel_hi:[1,0,1]
	v_pk_fma_f32 v[62:63], v[62:63], v[186:187], v[38:39] op_sel_hi:[1,0,1]
	v_pk_fma_f32 v[56:57], v[56:57], v[186:187], v[32:33] op_sel_hi:[1,0,1]
	v_pk_fma_f32 v[58:59], v[58:59], v[186:187], v[34:35] op_sel_hi:[1,0,1]
	v_pk_fma_f32 v[52:53], v[52:53], v[186:187], v[28:29] op_sel_hi:[1,0,1]
	v_pk_fma_f32 v[54:55], v[54:55], v[186:187], v[30:31] op_sel_hi:[1,0,1]
	v_pk_fma_f32 v[48:49], v[48:49], v[186:187], v[24:25] op_sel_hi:[1,0,1]
	v_pk_fma_f32 v[50:51], v[50:51], v[186:187], v[26:27] op_sel_hi:[1,0,1]
	v_pk_fma_f32 v[44:45], v[44:45], v[196:197], v[36:37] op_sel_hi:[1,0,1]
	v_pk_fma_f32 v[46:47], v[46:47], v[196:197], v[38:39] op_sel_hi:[1,0,1]
	v_pk_fma_f32 v[40:41], v[40:41], v[196:197], v[32:33] op_sel_hi:[1,0,1]
	v_pk_fma_f32 v[42:43], v[42:43], v[196:197], v[34:35] op_sel_hi:[1,0,1]
	v_pk_fma_f32 v[20:21], v[20:21], v[196:197], v[28:29] op_sel_hi:[1,0,1]
	v_pk_fma_f32 v[22:23], v[22:23], v[196:197], v[30:31] op_sel_hi:[1,0,1]
	v_pk_fma_f32 v[16:17], v[16:17], v[196:197], v[24:25] op_sel_hi:[1,0,1]
	v_pk_fma_f32 v[18:19], v[18:19], v[196:197], v[26:27] op_sel_hi:[1,0,1]
	v_pk_fma_f32 v[12:13], v[12:13], v[184:185], v[36:37] op_sel_hi:[1,0,1]
	v_pk_fma_f32 v[14:15], v[14:15], v[184:185], v[38:39] op_sel_hi:[1,0,1]
	v_pk_fma_f32 v[8:9], v[8:9], v[184:185], v[32:33] op_sel_hi:[1,0,1]
	v_pk_fma_f32 v[10:11], v[10:11], v[184:185], v[34:35] op_sel_hi:[1,0,1]
	v_pk_fma_f32 v[4:5], v[4:5], v[184:185], v[28:29] op_sel_hi:[1,0,1]
	v_pk_fma_f32 v[6:7], v[6:7], v[184:185], v[30:31] op_sel_hi:[1,0,1]
	v_pk_fma_f32 v[0:1], v[0:1], v[184:185], v[24:25] op_sel_hi:[1,0,1]
	v_pk_fma_f32 v[2:3], v[2:3], v[184:185], v[26:27] op_sel_hi:[1,0,1]
	v_pk_mul_f32 v[24:25], v[140:141], v[140:141]
	v_pk_mul_f32 v[26:27], v[142:143], v[142:143]
	v_pk_mul_f32 v[28:29], v[136:137], v[136:137]
	v_pk_mul_f32 v[30:31], v[138:139], v[138:139]
	v_pk_mul_f32 v[32:33], v[132:133], v[132:133]
	v_pk_mul_f32 v[34:35], v[134:135], v[134:135]
	v_pk_mul_f32 v[36:37], v[128:129], v[128:129]
	v_pk_mul_f32 v[38:39], v[130:131], v[130:131]
	v_pk_fma_f32 v[24:25], v[24:25], v[182:183], v[180:181]
	v_pk_fma_f32 v[26:27], v[26:27], v[182:183], v[180:181]
	v_pk_fma_f32 v[28:29], v[28:29], v[182:183], v[180:181]
	v_pk_fma_f32 v[30:31], v[30:31], v[182:183], v[180:181]
	v_pk_fma_f32 v[32:33], v[32:33], v[182:183], v[180:181]
	v_pk_fma_f32 v[34:35], v[34:35], v[182:183], v[180:181]
	v_pk_fma_f32 v[36:37], v[36:37], v[182:183], v[180:181]
	v_pk_fma_f32 v[38:39], v[38:39], v[182:183], v[180:181]
	v_pk_mul_f32 v[24:25], v[24:25], v[140:141]
	v_pk_mul_f32 v[26:27], v[26:27], v[142:143]
	v_pk_mul_f32 v[28:29], v[28:29], v[136:137]
	v_pk_mul_f32 v[30:31], v[30:31], v[138:139]
	v_pk_mul_f32 v[32:33], v[32:33], v[132:133]
	v_pk_mul_f32 v[34:35], v[34:35], v[134:135]
	v_pk_mul_f32 v[36:37], v[36:37], v[128:129]
	v_pk_mul_f32 v[38:39], v[38:39], v[130:131]
	v_exp_f32_e32 v24, v24
	v_exp_f32_e32 v25, v25
	v_exp_f32_e32 v26, v26
	v_exp_f32_e32 v27, v27
	v_exp_f32_e32 v28, v28
	v_exp_f32_e32 v29, v29
	v_exp_f32_e32 v30, v30
	v_exp_f32_e32 v31, v31
	v_exp_f32_e32 v32, v32
	v_exp_f32_e32 v33, v33
	v_exp_f32_e32 v34, v34
	v_exp_f32_e32 v35, v35
	v_exp_f32_e32 v36, v36
	v_exp_f32_e32 v37, v37
	v_exp_f32_e32 v38, v38
	v_exp_f32_e32 v39, v39
	v_pk_add_f32 v[24:25], v[24:25], 1.0 op_sel_hi:[1,0]
	v_pk_add_f32 v[26:27], v[26:27], 1.0 op_sel_hi:[1,0]
	v_pk_add_f32 v[28:29], v[28:29], 1.0 op_sel_hi:[1,0]
	v_pk_add_f32 v[30:31], v[30:31], 1.0 op_sel_hi:[1,0]
	v_pk_add_f32 v[32:33], v[32:33], 1.0 op_sel_hi:[1,0]
	v_pk_add_f32 v[34:35], v[34:35], 1.0 op_sel_hi:[1,0]
	v_pk_add_f32 v[36:37], v[36:37], 1.0 op_sel_hi:[1,0]
	v_pk_add_f32 v[38:39], v[38:39], 1.0 op_sel_hi:[1,0]
	v_rcp_f32_e32 v24, v24
	v_rcp_f32_e32 v25, v25
	v_rcp_f32_e32 v26, v26
	v_rcp_f32_e32 v27, v27
	v_rcp_f32_e32 v28, v28
	v_rcp_f32_e32 v29, v29
	v_rcp_f32_e32 v30, v30
	v_rcp_f32_e32 v31, v31
	v_rcp_f32_e32 v32, v32
	v_rcp_f32_e32 v33, v33
	v_rcp_f32_e32 v34, v34
	v_rcp_f32_e32 v35, v35
	v_rcp_f32_e32 v36, v36
	v_rcp_f32_e32 v37, v37
	v_rcp_f32_e32 v38, v38
	v_rcp_f32_e32 v39, v39
	v_pk_mul_f32 v[140:141], v[140:141], v[24:25]
	v_pk_mul_f32 v[142:143], v[142:143], v[26:27]
	v_pk_mul_f32 v[136:137], v[136:137], v[28:29]
	v_pk_mul_f32 v[138:139], v[138:139], v[30:31]
	v_pk_mul_f32 v[132:133], v[132:133], v[32:33]
	v_pk_mul_f32 v[134:135], v[134:135], v[34:35]
	v_pk_mul_f32 v[128:129], v[128:129], v[36:37]
	v_pk_mul_f32 v[130:131], v[130:131], v[38:39]
	v_cvt_pk_bf16_f32 v24, v140, v141
	v_cvt_pk_bf16_f32 v25, v142, v143
	v_cvt_pk_bf16_f32 v26, v136, v137
	v_cvt_pk_bf16_f32 v27, v138, v139
	v_cvt_pk_bf16_f32 v28, v132, v133
	v_cvt_pk_bf16_f32 v29, v134, v135
	v_cvt_pk_bf16_f32 v30, v128, v129
	v_cvt_pk_bf16_f32 v31, v130, v131
	global_store_dwordx4 v[160:161], v[24:27], off
	global_store_dwordx4 v[160:161], v[28:31], off offset:256
	s_and_b64 vcc, exec, s[20:21]
	s_cbranch_vccz .Lio_skip_0
	v_pk_mul_f32 v[32:33], v[140:141], v[140:141]
	v_pk_fma_f32 v[32:33], v[142:143], v[142:143], v[32:33]
	v_pk_fma_f32 v[32:33], v[136:137], v[136:137], v[32:33]
	v_pk_fma_f32 v[32:33], v[138:139], v[138:139], v[32:33]
	v_pk_fma_f32 v[32:33], v[132:133], v[132:133], v[32:33]
	v_pk_fma_f32 v[32:33], v[134:135], v[134:135], v[32:33]
	v_pk_fma_f32 v[32:33], v[128:129], v[128:129], v[32:33]
	v_pk_fma_f32 v[32:33], v[130:131], v[130:131], v[32:33]
	s_nop 0
	v_add_f32_e32 v32, v32, v33
	v_mov_b32_e32 v33, v32
	s_nop 1
	v_permlane16_swap_b32_e32 v32, v33
	v_add_f32_e32 v32, v32, v33
	v_mov_b32_e32 v33, v32
	s_nop 1
	v_permlane32_swap_b32_e32 v32, v33
	s_and_saveexec_b64 vcc, s[6:7]
	v_add_f32_e32 v32, v32, v33
	global_atomic_add_f32 v[156:157], v32, off
	s_mov_b64 exec, vcc
.Lio_skip_0:
	v_lshl_add_u64 v[160:161], v[160:161], 0, s[2:3]
	s_nop 1
	v_pk_mul_f32 v[24:25], v[124:125], v[124:125]
	v_pk_mul_f32 v[26:27], v[126:127], v[126:127]
	v_pk_mul_f32 v[28:29], v[120:121], v[120:121]
	v_pk_mul_f32 v[30:31], v[122:123], v[122:123]
	v_pk_mul_f32 v[32:33], v[116:117], v[116:117]
	v_pk_mul_f32 v[34:35], v[118:119], v[118:119]
	v_pk_mul_f32 v[36:37], v[112:113], v[112:113]
	v_pk_mul_f32 v[38:39], v[114:115], v[114:115]
	v_pk_fma_f32 v[24:25], v[24:25], v[182:183], v[180:181]
	v_pk_fma_f32 v[26:27], v[26:27], v[182:183], v[180:181]
	v_pk_fma_f32 v[28:29], v[28:29], v[182:183], v[180:181]
	v_pk_fma_f32 v[30:31], v[30:31], v[182:183], v[180:181]
	v_pk_fma_f32 v[32:33], v[32:33], v[182:183], v[180:181]
	v_pk_fma_f32 v[34:35], v[34:35], v[182:183], v[180:181]
	v_pk_fma_f32 v[36:37], v[36:37], v[182:183], v[180:181]
	v_pk_fma_f32 v[38:39], v[38:39], v[182:183], v[180:181]
	v_pk_mul_f32 v[24:25], v[24:25], v[124:125]
	v_pk_mul_f32 v[26:27], v[26:27], v[126:127]
	v_pk_mul_f32 v[28:29], v[28:29], v[120:121]
	v_pk_mul_f32 v[30:31], v[30:31], v[122:123]
	v_pk_mul_f32 v[32:33], v[32:33], v[116:117]
	v_pk_mul_f32 v[34:35], v[34:35], v[118:119]
	v_pk_mul_f32 v[36:37], v[36:37], v[112:113]
	v_pk_mul_f32 v[38:39], v[38:39], v[114:115]
	v_exp_f32_e32 v24, v24
	v_exp_f32_e32 v25, v25
	v_exp_f32_e32 v26, v26
	v_exp_f32_e32 v27, v27
	v_exp_f32_e32 v28, v28
	v_exp_f32_e32 v29, v29
	v_exp_f32_e32 v30, v30
	v_exp_f32_e32 v31, v31
	v_exp_f32_e32 v32, v32
	v_exp_f32_e32 v33, v33
	v_exp_f32_e32 v34, v34
	v_exp_f32_e32 v35, v35
	v_exp_f32_e32 v36, v36
	v_exp_f32_e32 v37, v37
	v_exp_f32_e32 v38, v38
	v_exp_f32_e32 v39, v39
	v_pk_add_f32 v[24:25], v[24:25], 1.0 op_sel_hi:[1,0]
	v_pk_add_f32 v[26:27], v[26:27], 1.0 op_sel_hi:[1,0]
	v_pk_add_f32 v[28:29], v[28:29], 1.0 op_sel_hi:[1,0]
	v_pk_add_f32 v[30:31], v[30:31], 1.0 op_sel_hi:[1,0]
	v_pk_add_f32 v[32:33], v[32:33], 1.0 op_sel_hi:[1,0]
	v_pk_add_f32 v[34:35], v[34:35], 1.0 op_sel_hi:[1,0]
	v_pk_add_f32 v[36:37], v[36:37], 1.0 op_sel_hi:[1,0]
	v_pk_add_f32 v[38:39], v[38:39], 1.0 op_sel_hi:[1,0]
	v_rcp_f32_e32 v24, v24
	v_rcp_f32_e32 v25, v25
	v_rcp_f32_e32 v26, v26
	v_rcp_f32_e32 v27, v27
	v_rcp_f32_e32 v28, v28
	v_rcp_f32_e32 v29, v29
	v_rcp_f32_e32 v30, v30
	v_rcp_f32_e32 v31, v31
	v_rcp_f32_e32 v32, v32
	v_rcp_f32_e32 v33, v33
	v_rcp_f32_e32 v34, v34
	v_rcp_f32_e32 v35, v35
	v_rcp_f32_e32 v36, v36
	v_rcp_f32_e32 v37, v37
	v_rcp_f32_e32 v38, v38
	v_rcp_f32_e32 v39, v39
	v_pk_mul_f32 v[124:125], v[124:125], v[24:25]
	v_pk_mul_f32 v[126:127], v[126:127], v[26:27]
	v_pk_mul_f32 v[120:121], v[120:121], v[28:29]
	v_pk_mul_f32 v[122:123], v[122:123], v[30:31]
	v_pk_mul_f32 v[116:117], v[116:117], v[32:33]
	v_pk_mul_f32 v[118:119], v[118:119], v[34:35]
	v_pk_mul_f32 v[112:113], v[112:113], v[36:37]
	v_pk_mul_f32 v[114:115], v[114:115], v[38:39]
	v_cvt_pk_bf16_f32 v24, v124, v125
	v_cvt_pk_bf16_f32 v25, v126, v127
	v_cvt_pk_bf16_f32 v26, v120, v121
	v_cvt_pk_bf16_f32 v27, v122, v123
	v_cvt_pk_bf16_f32 v28, v116, v117
	v_cvt_pk_bf16_f32 v29, v118, v119
	v_cvt_pk_bf16_f32 v30, v112, v113
	v_cvt_pk_bf16_f32 v31, v114, v115
	global_store_dwordx4 v[160:161], v[24:27], off
	global_store_dwordx4 v[160:161], v[28:31], off offset:256
	s_and_b64 vcc, exec, s[20:21]
	s_cbranch_vccz .Lio_skip_1
	v_pk_mul_f32 v[32:33], v[124:125], v[124:125]
	v_pk_fma_f32 v[32:33], v[126:127], v[126:127], v[32:33]
	v_pk_fma_f32 v[32:33], v[120:121], v[120:121], v[32:33]
	v_pk_fma_f32 v[32:33], v[122:123], v[122:123], v[32:33]
	v_pk_fma_f32 v[32:33], v[116:117], v[116:117], v[32:33]
	v_pk_fma_f32 v[32:33], v[118:119], v[118:119], v[32:33]
	v_pk_fma_f32 v[32:33], v[112:113], v[112:113], v[32:33]
	v_pk_fma_f32 v[32:33], v[114:115], v[114:115], v[32:33]
	s_nop 0
	v_add_f32_e32 v32, v32, v33
	v_mov_b32_e32 v33, v32
	s_nop 1
	v_permlane16_swap_b32_e32 v32, v33
	v_add_f32_e32 v32, v32, v33
	v_mov_b32_e32 v33, v32
	s_nop 1
	v_permlane32_swap_b32_e32 v32, v33
	s_and_saveexec_b64 vcc, s[6:7]
	v_add_f32_e32 v32, v32, v33
	global_atomic_add_f32 v[156:157], v32, off offset:64
	s_mov_b64 exec, vcc
.Lio_skip_1:
	v_lshl_add_u64 v[160:161], v[160:161], 0, s[2:3]
	s_nop 1
	v_pk_mul_f32 v[24:25], v[108:109], v[108:109]
	v_pk_mul_f32 v[26:27], v[110:111], v[110:111]
	v_pk_mul_f32 v[28:29], v[104:105], v[104:105]
	v_pk_mul_f32 v[30:31], v[106:107], v[106:107]
	v_pk_mul_f32 v[32:33], v[100:101], v[100:101]
	v_pk_mul_f32 v[34:35], v[102:103], v[102:103]
	v_pk_mul_f32 v[36:37], v[96:97], v[96:97]
	v_pk_mul_f32 v[38:39], v[98:99], v[98:99]
	v_pk_fma_f32 v[24:25], v[24:25], v[182:183], v[180:181]
	v_pk_fma_f32 v[26:27], v[26:27], v[182:183], v[180:181]
	v_pk_fma_f32 v[28:29], v[28:29], v[182:183], v[180:181]
	v_pk_fma_f32 v[30:31], v[30:31], v[182:183], v[180:181]
	v_pk_fma_f32 v[32:33], v[32:33], v[182:183], v[180:181]
	v_pk_fma_f32 v[34:35], v[34:35], v[182:183], v[180:181]
	v_pk_fma_f32 v[36:37], v[36:37], v[182:183], v[180:181]
	v_pk_fma_f32 v[38:39], v[38:39], v[182:183], v[180:181]
	v_pk_mul_f32 v[24:25], v[24:25], v[108:109]
	v_pk_mul_f32 v[26:27], v[26:27], v[110:111]
	v_pk_mul_f32 v[28:29], v[28:29], v[104:105]
	v_pk_mul_f32 v[30:31], v[30:31], v[106:107]
	v_pk_mul_f32 v[32:33], v[32:33], v[100:101]
	v_pk_mul_f32 v[34:35], v[34:35], v[102:103]
	v_pk_mul_f32 v[36:37], v[36:37], v[96:97]
	v_pk_mul_f32 v[38:39], v[38:39], v[98:99]
	v_exp_f32_e32 v24, v24
	v_exp_f32_e32 v25, v25
	v_exp_f32_e32 v26, v26
	v_exp_f32_e32 v27, v27
	v_exp_f32_e32 v28, v28
	v_exp_f32_e32 v29, v29
	v_exp_f32_e32 v30, v30
	v_exp_f32_e32 v31, v31
	v_exp_f32_e32 v32, v32
	v_exp_f32_e32 v33, v33
	v_exp_f32_e32 v34, v34
	v_exp_f32_e32 v35, v35
	v_exp_f32_e32 v36, v36
	v_exp_f32_e32 v37, v37
	v_exp_f32_e32 v38, v38
	v_exp_f32_e32 v39, v39
	v_pk_add_f32 v[24:25], v[24:25], 1.0 op_sel_hi:[1,0]
	v_pk_add_f32 v[26:27], v[26:27], 1.0 op_sel_hi:[1,0]
	v_pk_add_f32 v[28:29], v[28:29], 1.0 op_sel_hi:[1,0]
	v_pk_add_f32 v[30:31], v[30:31], 1.0 op_sel_hi:[1,0]
	v_pk_add_f32 v[32:33], v[32:33], 1.0 op_sel_hi:[1,0]
	v_pk_add_f32 v[34:35], v[34:35], 1.0 op_sel_hi:[1,0]
	v_pk_add_f32 v[36:37], v[36:37], 1.0 op_sel_hi:[1,0]
	v_pk_add_f32 v[38:39], v[38:39], 1.0 op_sel_hi:[1,0]
	v_rcp_f32_e32 v24, v24
	v_rcp_f32_e32 v25, v25
	v_rcp_f32_e32 v26, v26
	v_rcp_f32_e32 v27, v27
	v_rcp_f32_e32 v28, v28
	v_rcp_f32_e32 v29, v29
	v_rcp_f32_e32 v30, v30
	v_rcp_f32_e32 v31, v31
	v_rcp_f32_e32 v32, v32
	v_rcp_f32_e32 v33, v33
	v_rcp_f32_e32 v34, v34
	v_rcp_f32_e32 v35, v35
	v_rcp_f32_e32 v36, v36
	v_rcp_f32_e32 v37, v37
	v_rcp_f32_e32 v38, v38
	v_rcp_f32_e32 v39, v39
	v_pk_mul_f32 v[108:109], v[108:109], v[24:25]
	v_pk_mul_f32 v[110:111], v[110:111], v[26:27]
	v_pk_mul_f32 v[104:105], v[104:105], v[28:29]
	v_pk_mul_f32 v[106:107], v[106:107], v[30:31]
	v_pk_mul_f32 v[100:101], v[100:101], v[32:33]
	v_pk_mul_f32 v[102:103], v[102:103], v[34:35]
	v_pk_mul_f32 v[96:97], v[96:97], v[36:37]
	v_pk_mul_f32 v[98:99], v[98:99], v[38:39]
	v_cvt_pk_bf16_f32 v24, v108, v109
	v_cvt_pk_bf16_f32 v25, v110, v111
	v_cvt_pk_bf16_f32 v26, v104, v105
	v_cvt_pk_bf16_f32 v27, v106, v107
	v_cvt_pk_bf16_f32 v28, v100, v101
	v_cvt_pk_bf16_f32 v29, v102, v103
	v_cvt_pk_bf16_f32 v30, v96, v97
	v_cvt_pk_bf16_f32 v31, v98, v99
	global_store_dwordx4 v[160:161], v[24:27], off
	global_store_dwordx4 v[160:161], v[28:31], off offset:256
	s_and_b64 vcc, exec, s[20:21]
	s_cbranch_vccz .Lio_skip_2
	v_pk_mul_f32 v[32:33], v[108:109], v[108:109]
	v_pk_fma_f32 v[32:33], v[110:111], v[110:111], v[32:33]
	v_pk_fma_f32 v[32:33], v[104:105], v[104:105], v[32:33]
	v_pk_fma_f32 v[32:33], v[106:107], v[106:107], v[32:33]
	v_pk_fma_f32 v[32:33], v[100:101], v[100:101], v[32:33]
	v_pk_fma_f32 v[32:33], v[102:103], v[102:103], v[32:33]
	v_pk_fma_f32 v[32:33], v[96:97], v[96:97], v[32:33]
	v_pk_fma_f32 v[32:33], v[98:99], v[98:99], v[32:33]
	s_nop 0
	v_add_f32_e32 v32, v32, v33
	v_mov_b32_e32 v33, v32
	s_nop 1
	v_permlane16_swap_b32_e32 v32, v33
	v_add_f32_e32 v32, v32, v33
	v_mov_b32_e32 v33, v32
	s_nop 1
	v_permlane32_swap_b32_e32 v32, v33
	s_and_saveexec_b64 vcc, s[6:7]
	v_add_f32_e32 v32, v32, v33
	global_atomic_add_f32 v[156:157], v32, off offset:128
	s_mov_b64 exec, vcc
.Lio_skip_2:
	v_lshl_add_u64 v[160:161], v[160:161], 0, s[2:3]
	s_nop 1
	v_pk_mul_f32 v[24:25], v[92:93], v[92:93]
	v_pk_mul_f32 v[26:27], v[94:95], v[94:95]
	v_pk_mul_f32 v[28:29], v[88:89], v[88:89]
	v_pk_mul_f32 v[30:31], v[90:91], v[90:91]
	v_pk_mul_f32 v[32:33], v[84:85], v[84:85]
	v_pk_mul_f32 v[34:35], v[86:87], v[86:87]
	v_pk_mul_f32 v[36:37], v[80:81], v[80:81]
	v_pk_mul_f32 v[38:39], v[82:83], v[82:83]
	v_pk_fma_f32 v[24:25], v[24:25], v[182:183], v[180:181]
	v_pk_fma_f32 v[26:27], v[26:27], v[182:183], v[180:181]
	v_pk_fma_f32 v[28:29], v[28:29], v[182:183], v[180:181]
	v_pk_fma_f32 v[30:31], v[30:31], v[182:183], v[180:181]
	v_pk_fma_f32 v[32:33], v[32:33], v[182:183], v[180:181]
	v_pk_fma_f32 v[34:35], v[34:35], v[182:183], v[180:181]
	v_pk_fma_f32 v[36:37], v[36:37], v[182:183], v[180:181]
	v_pk_fma_f32 v[38:39], v[38:39], v[182:183], v[180:181]
	v_pk_mul_f32 v[24:25], v[24:25], v[92:93]
	v_pk_mul_f32 v[26:27], v[26:27], v[94:95]
	v_pk_mul_f32 v[28:29], v[28:29], v[88:89]
	v_pk_mul_f32 v[30:31], v[30:31], v[90:91]
	v_pk_mul_f32 v[32:33], v[32:33], v[84:85]
	v_pk_mul_f32 v[34:35], v[34:35], v[86:87]
	v_pk_mul_f32 v[36:37], v[36:37], v[80:81]
	v_pk_mul_f32 v[38:39], v[38:39], v[82:83]
	v_exp_f32_e32 v24, v24
	v_exp_f32_e32 v25, v25
	v_exp_f32_e32 v26, v26
	v_exp_f32_e32 v27, v27
	v_exp_f32_e32 v28, v28
	v_exp_f32_e32 v29, v29
	v_exp_f32_e32 v30, v30
	v_exp_f32_e32 v31, v31
	v_exp_f32_e32 v32, v32
	v_exp_f32_e32 v33, v33
	v_exp_f32_e32 v34, v34
	v_exp_f32_e32 v35, v35
	v_exp_f32_e32 v36, v36
	v_exp_f32_e32 v37, v37
	v_exp_f32_e32 v38, v38
	v_exp_f32_e32 v39, v39
	v_pk_add_f32 v[24:25], v[24:25], 1.0 op_sel_hi:[1,0]
	v_pk_add_f32 v[26:27], v[26:27], 1.0 op_sel_hi:[1,0]
	v_pk_add_f32 v[28:29], v[28:29], 1.0 op_sel_hi:[1,0]
	v_pk_add_f32 v[30:31], v[30:31], 1.0 op_sel_hi:[1,0]
	v_pk_add_f32 v[32:33], v[32:33], 1.0 op_sel_hi:[1,0]
	v_pk_add_f32 v[34:35], v[34:35], 1.0 op_sel_hi:[1,0]
	v_pk_add_f32 v[36:37], v[36:37], 1.0 op_sel_hi:[1,0]
	v_pk_add_f32 v[38:39], v[38:39], 1.0 op_sel_hi:[1,0]
	v_rcp_f32_e32 v24, v24
	v_rcp_f32_e32 v25, v25
	v_rcp_f32_e32 v26, v26
	v_rcp_f32_e32 v27, v27
	v_rcp_f32_e32 v28, v28
	v_rcp_f32_e32 v29, v29
	v_rcp_f32_e32 v30, v30
	v_rcp_f32_e32 v31, v31
	v_rcp_f32_e32 v32, v32
	v_rcp_f32_e32 v33, v33
	v_rcp_f32_e32 v34, v34
	v_rcp_f32_e32 v35, v35
	v_rcp_f32_e32 v36, v36
	v_rcp_f32_e32 v37, v37
	v_rcp_f32_e32 v38, v38
	v_rcp_f32_e32 v39, v39
	v_pk_mul_f32 v[92:93], v[92:93], v[24:25]
	v_pk_mul_f32 v[94:95], v[94:95], v[26:27]
	v_pk_mul_f32 v[88:89], v[88:89], v[28:29]
	v_pk_mul_f32 v[90:91], v[90:91], v[30:31]
	v_pk_mul_f32 v[84:85], v[84:85], v[32:33]
	v_pk_mul_f32 v[86:87], v[86:87], v[34:35]
	v_pk_mul_f32 v[80:81], v[80:81], v[36:37]
	v_pk_mul_f32 v[82:83], v[82:83], v[38:39]
	v_cvt_pk_bf16_f32 v24, v92, v93
	v_cvt_pk_bf16_f32 v25, v94, v95
	v_cvt_pk_bf16_f32 v26, v88, v89
	v_cvt_pk_bf16_f32 v27, v90, v91
	v_cvt_pk_bf16_f32 v28, v84, v85
	v_cvt_pk_bf16_f32 v29, v86, v87
	v_cvt_pk_bf16_f32 v30, v80, v81
	v_cvt_pk_bf16_f32 v31, v82, v83
	global_store_dwordx4 v[160:161], v[24:27], off
	global_store_dwordx4 v[160:161], v[28:31], off offset:256
	s_and_b64 vcc, exec, s[20:21]
	s_cbranch_vccz .Lio_skip_3
	v_pk_mul_f32 v[32:33], v[92:93], v[92:93]
	v_pk_fma_f32 v[32:33], v[94:95], v[94:95], v[32:33]
	v_pk_fma_f32 v[32:33], v[88:89], v[88:89], v[32:33]
	v_pk_fma_f32 v[32:33], v[90:91], v[90:91], v[32:33]
	v_pk_fma_f32 v[32:33], v[84:85], v[84:85], v[32:33]
	v_pk_fma_f32 v[32:33], v[86:87], v[86:87], v[32:33]
	v_pk_fma_f32 v[32:33], v[80:81], v[80:81], v[32:33]
	v_pk_fma_f32 v[32:33], v[82:83], v[82:83], v[32:33]
	s_nop 0
	v_add_f32_e32 v32, v32, v33
	v_mov_b32_e32 v33, v32
	s_nop 1
	v_permlane16_swap_b32_e32 v32, v33
	v_add_f32_e32 v32, v32, v33
	v_mov_b32_e32 v33, v32
	s_nop 1
	v_permlane32_swap_b32_e32 v32, v33
	s_and_saveexec_b64 vcc, s[6:7]
	v_add_f32_e32 v32, v32, v33
	global_atomic_add_f32 v[156:157], v32, off offset:192
	s_mov_b64 exec, vcc
.Lio_skip_3:
	v_lshl_add_u64 v[160:161], v[160:161], 0, s[50:51]
	s_nop 1
	v_pk_mul_f32 v[24:25], v[76:77], v[76:77]
	v_pk_mul_f32 v[26:27], v[78:79], v[78:79]
	v_pk_mul_f32 v[28:29], v[72:73], v[72:73]
	v_pk_mul_f32 v[30:31], v[74:75], v[74:75]
	v_pk_mul_f32 v[32:33], v[68:69], v[68:69]
	v_pk_mul_f32 v[34:35], v[70:71], v[70:71]
	v_pk_mul_f32 v[36:37], v[64:65], v[64:65]
	v_pk_mul_f32 v[38:39], v[66:67], v[66:67]
	v_pk_fma_f32 v[24:25], v[24:25], v[182:183], v[180:181]
	v_pk_fma_f32 v[26:27], v[26:27], v[182:183], v[180:181]
	v_pk_fma_f32 v[28:29], v[28:29], v[182:183], v[180:181]
	v_pk_fma_f32 v[30:31], v[30:31], v[182:183], v[180:181]
	v_pk_fma_f32 v[32:33], v[32:33], v[182:183], v[180:181]
	v_pk_fma_f32 v[34:35], v[34:35], v[182:183], v[180:181]
	v_pk_fma_f32 v[36:37], v[36:37], v[182:183], v[180:181]
	v_pk_fma_f32 v[38:39], v[38:39], v[182:183], v[180:181]
	v_pk_mul_f32 v[24:25], v[24:25], v[76:77]
	v_pk_mul_f32 v[26:27], v[26:27], v[78:79]
	v_pk_mul_f32 v[28:29], v[28:29], v[72:73]
	v_pk_mul_f32 v[30:31], v[30:31], v[74:75]
	v_pk_mul_f32 v[32:33], v[32:33], v[68:69]
	v_pk_mul_f32 v[34:35], v[34:35], v[70:71]
	v_pk_mul_f32 v[36:37], v[36:37], v[64:65]
	v_pk_mul_f32 v[38:39], v[38:39], v[66:67]
	v_exp_f32_e32 v24, v24
	v_exp_f32_e32 v25, v25
	v_exp_f32_e32 v26, v26
	v_exp_f32_e32 v27, v27
	v_exp_f32_e32 v28, v28
	v_exp_f32_e32 v29, v29
	v_exp_f32_e32 v30, v30
	v_exp_f32_e32 v31, v31
	v_exp_f32_e32 v32, v32
	v_exp_f32_e32 v33, v33
	v_exp_f32_e32 v34, v34
	v_exp_f32_e32 v35, v35
	v_exp_f32_e32 v36, v36
	v_exp_f32_e32 v37, v37
	v_exp_f32_e32 v38, v38
	v_exp_f32_e32 v39, v39
	v_pk_add_f32 v[24:25], v[24:25], 1.0 op_sel_hi:[1,0]
	v_pk_add_f32 v[26:27], v[26:27], 1.0 op_sel_hi:[1,0]
	v_pk_add_f32 v[28:29], v[28:29], 1.0 op_sel_hi:[1,0]
	v_pk_add_f32 v[30:31], v[30:31], 1.0 op_sel_hi:[1,0]
	v_pk_add_f32 v[32:33], v[32:33], 1.0 op_sel_hi:[1,0]
	v_pk_add_f32 v[34:35], v[34:35], 1.0 op_sel_hi:[1,0]
	v_pk_add_f32 v[36:37], v[36:37], 1.0 op_sel_hi:[1,0]
	v_pk_add_f32 v[38:39], v[38:39], 1.0 op_sel_hi:[1,0]
	v_rcp_f32_e32 v24, v24
	v_rcp_f32_e32 v25, v25
	v_rcp_f32_e32 v26, v26
	v_rcp_f32_e32 v27, v27
	v_rcp_f32_e32 v28, v28
	v_rcp_f32_e32 v29, v29
	v_rcp_f32_e32 v30, v30
	v_rcp_f32_e32 v31, v31
	v_rcp_f32_e32 v32, v32
	v_rcp_f32_e32 v33, v33
	v_rcp_f32_e32 v34, v34
	v_rcp_f32_e32 v35, v35
	v_rcp_f32_e32 v36, v36
	v_rcp_f32_e32 v37, v37
	v_rcp_f32_e32 v38, v38
	v_rcp_f32_e32 v39, v39
	v_pk_mul_f32 v[76:77], v[76:77], v[24:25]
	v_pk_mul_f32 v[78:79], v[78:79], v[26:27]
	v_pk_mul_f32 v[72:73], v[72:73], v[28:29]
	v_pk_mul_f32 v[74:75], v[74:75], v[30:31]
	v_pk_mul_f32 v[68:69], v[68:69], v[32:33]
	v_pk_mul_f32 v[70:71], v[70:71], v[34:35]
	v_pk_mul_f32 v[64:65], v[64:65], v[36:37]
	v_pk_mul_f32 v[66:67], v[66:67], v[38:39]
	v_cvt_pk_bf16_f32 v24, v76, v77
	v_cvt_pk_bf16_f32 v25, v78, v79
	v_cvt_pk_bf16_f32 v26, v72, v73
	v_cvt_pk_bf16_f32 v27, v74, v75
	v_cvt_pk_bf16_f32 v28, v68, v69
	v_cvt_pk_bf16_f32 v29, v70, v71
	v_cvt_pk_bf16_f32 v30, v64, v65
	v_cvt_pk_bf16_f32 v31, v66, v67
	global_store_dwordx4 v[160:161], v[24:27], off
	global_store_dwordx4 v[160:161], v[28:31], off offset:256
	s_and_b64 vcc, exec, s[20:21]
	s_cbranch_vccz .Lio_skip_4
	v_pk_mul_f32 v[32:33], v[76:77], v[76:77]
	v_pk_fma_f32 v[32:33], v[78:79], v[78:79], v[32:33]
	v_pk_fma_f32 v[32:33], v[72:73], v[72:73], v[32:33]
	v_pk_fma_f32 v[32:33], v[74:75], v[74:75], v[32:33]
	v_pk_fma_f32 v[32:33], v[68:69], v[68:69], v[32:33]
	v_pk_fma_f32 v[32:33], v[70:71], v[70:71], v[32:33]
	v_pk_fma_f32 v[32:33], v[64:65], v[64:65], v[32:33]
	v_pk_fma_f32 v[32:33], v[66:67], v[66:67], v[32:33]
	s_nop 0
	v_add_f32_e32 v32, v32, v33
	v_mov_b32_e32 v33, v32
	s_nop 1
	v_permlane16_swap_b32_e32 v32, v33
	v_add_f32_e32 v32, v32, v33
	v_mov_b32_e32 v33, v32
	s_nop 1
	v_permlane32_swap_b32_e32 v32, v33
	s_and_saveexec_b64 vcc, s[6:7]
	v_add_f32_e32 v32, v32, v33
	global_atomic_add_f32 v[156:157], v32, off offset:512
	s_mov_b64 exec, vcc
.Lio_skip_4:
	v_lshl_add_u64 v[160:161], v[160:161], 0, s[2:3]
	s_nop 1
	v_pk_mul_f32 v[24:25], v[60:61], v[60:61]
	v_pk_mul_f32 v[26:27], v[62:63], v[62:63]
	v_pk_mul_f32 v[28:29], v[56:57], v[56:57]
	v_pk_mul_f32 v[30:31], v[58:59], v[58:59]
	v_pk_mul_f32 v[32:33], v[52:53], v[52:53]
	v_pk_mul_f32 v[34:35], v[54:55], v[54:55]
	v_pk_mul_f32 v[36:37], v[48:49], v[48:49]
	v_pk_mul_f32 v[38:39], v[50:51], v[50:51]
	v_pk_fma_f32 v[24:25], v[24:25], v[182:183], v[180:181]
	v_pk_fma_f32 v[26:27], v[26:27], v[182:183], v[180:181]
	v_pk_fma_f32 v[28:29], v[28:29], v[182:183], v[180:181]
	v_pk_fma_f32 v[30:31], v[30:31], v[182:183], v[180:181]
	v_pk_fma_f32 v[32:33], v[32:33], v[182:183], v[180:181]
	v_pk_fma_f32 v[34:35], v[34:35], v[182:183], v[180:181]
	v_pk_fma_f32 v[36:37], v[36:37], v[182:183], v[180:181]
	v_pk_fma_f32 v[38:39], v[38:39], v[182:183], v[180:181]
	v_pk_mul_f32 v[24:25], v[24:25], v[60:61]
	v_pk_mul_f32 v[26:27], v[26:27], v[62:63]
	v_pk_mul_f32 v[28:29], v[28:29], v[56:57]
	v_pk_mul_f32 v[30:31], v[30:31], v[58:59]
	v_pk_mul_f32 v[32:33], v[32:33], v[52:53]
	v_pk_mul_f32 v[34:35], v[34:35], v[54:55]
	v_pk_mul_f32 v[36:37], v[36:37], v[48:49]
	v_pk_mul_f32 v[38:39], v[38:39], v[50:51]
	v_exp_f32_e32 v24, v24
	v_exp_f32_e32 v25, v25
	v_exp_f32_e32 v26, v26
	v_exp_f32_e32 v27, v27
	v_exp_f32_e32 v28, v28
	v_exp_f32_e32 v29, v29
	v_exp_f32_e32 v30, v30
	v_exp_f32_e32 v31, v31
	v_exp_f32_e32 v32, v32
	v_exp_f32_e32 v33, v33
	v_exp_f32_e32 v34, v34
	v_exp_f32_e32 v35, v35
	v_exp_f32_e32 v36, v36
	v_exp_f32_e32 v37, v37
	v_exp_f32_e32 v38, v38
	v_exp_f32_e32 v39, v39
	v_pk_add_f32 v[24:25], v[24:25], 1.0 op_sel_hi:[1,0]
	v_pk_add_f32 v[26:27], v[26:27], 1.0 op_sel_hi:[1,0]
	v_pk_add_f32 v[28:29], v[28:29], 1.0 op_sel_hi:[1,0]
	v_pk_add_f32 v[30:31], v[30:31], 1.0 op_sel_hi:[1,0]
	v_pk_add_f32 v[32:33], v[32:33], 1.0 op_sel_hi:[1,0]
	v_pk_add_f32 v[34:35], v[34:35], 1.0 op_sel_hi:[1,0]
	v_pk_add_f32 v[36:37], v[36:37], 1.0 op_sel_hi:[1,0]
	v_pk_add_f32 v[38:39], v[38:39], 1.0 op_sel_hi:[1,0]
	v_rcp_f32_e32 v24, v24
	v_rcp_f32_e32 v25, v25
	v_rcp_f32_e32 v26, v26
	v_rcp_f32_e32 v27, v27
	v_rcp_f32_e32 v28, v28
	v_rcp_f32_e32 v29, v29
	v_rcp_f32_e32 v30, v30
	v_rcp_f32_e32 v31, v31
	v_rcp_f32_e32 v32, v32
	v_rcp_f32_e32 v33, v33
	v_rcp_f32_e32 v34, v34
	v_rcp_f32_e32 v35, v35
	v_rcp_f32_e32 v36, v36
	v_rcp_f32_e32 v37, v37
	v_rcp_f32_e32 v38, v38
	v_rcp_f32_e32 v39, v39
	v_pk_mul_f32 v[60:61], v[60:61], v[24:25]
	v_pk_mul_f32 v[62:63], v[62:63], v[26:27]
	v_pk_mul_f32 v[56:57], v[56:57], v[28:29]
	v_pk_mul_f32 v[58:59], v[58:59], v[30:31]
	v_pk_mul_f32 v[52:53], v[52:53], v[32:33]
	v_pk_mul_f32 v[54:55], v[54:55], v[34:35]
	v_pk_mul_f32 v[48:49], v[48:49], v[36:37]
	v_pk_mul_f32 v[50:51], v[50:51], v[38:39]
	v_cvt_pk_bf16_f32 v24, v60, v61
	v_cvt_pk_bf16_f32 v25, v62, v63
	v_cvt_pk_bf16_f32 v26, v56, v57
	v_cvt_pk_bf16_f32 v27, v58, v59
	v_cvt_pk_bf16_f32 v28, v52, v53
	v_cvt_pk_bf16_f32 v29, v54, v55
	v_cvt_pk_bf16_f32 v30, v48, v49
	v_cvt_pk_bf16_f32 v31, v50, v51
	global_store_dwordx4 v[160:161], v[24:27], off
	global_store_dwordx4 v[160:161], v[28:31], off offset:256
	s_and_b64 vcc, exec, s[20:21]
	s_cbranch_vccz .Lio_skip_5
	v_pk_mul_f32 v[32:33], v[60:61], v[60:61]
	v_pk_fma_f32 v[32:33], v[62:63], v[62:63], v[32:33]
	v_pk_fma_f32 v[32:33], v[56:57], v[56:57], v[32:33]
	v_pk_fma_f32 v[32:33], v[58:59], v[58:59], v[32:33]
	v_pk_fma_f32 v[32:33], v[52:53], v[52:53], v[32:33]
	v_pk_fma_f32 v[32:33], v[54:55], v[54:55], v[32:33]
	v_pk_fma_f32 v[32:33], v[48:49], v[48:49], v[32:33]
	v_pk_fma_f32 v[32:33], v[50:51], v[50:51], v[32:33]
	s_nop 0
	v_add_f32_e32 v32, v32, v33
	v_mov_b32_e32 v33, v32
	s_nop 1
	v_permlane16_swap_b32_e32 v32, v33
	v_add_f32_e32 v32, v32, v33
	v_mov_b32_e32 v33, v32
	s_nop 1
	v_permlane32_swap_b32_e32 v32, v33
	s_and_saveexec_b64 vcc, s[6:7]
	v_add_f32_e32 v32, v32, v33
	global_atomic_add_f32 v[156:157], v32, off offset:576
	s_mov_b64 exec, vcc
.Lio_skip_5:
	v_lshl_add_u64 v[160:161], v[160:161], 0, s[2:3]
	s_nop 1
	v_pk_mul_f32 v[24:25], v[44:45], v[44:45]
	v_pk_mul_f32 v[26:27], v[46:47], v[46:47]
	v_pk_mul_f32 v[28:29], v[40:41], v[40:41]
	v_pk_mul_f32 v[30:31], v[42:43], v[42:43]
	v_pk_mul_f32 v[32:33], v[20:21], v[20:21]
	v_pk_mul_f32 v[34:35], v[22:23], v[22:23]
	v_pk_mul_f32 v[36:37], v[16:17], v[16:17]
	v_pk_mul_f32 v[38:39], v[18:19], v[18:19]
	v_pk_fma_f32 v[24:25], v[24:25], v[182:183], v[180:181]
	v_pk_fma_f32 v[26:27], v[26:27], v[182:183], v[180:181]
	v_pk_fma_f32 v[28:29], v[28:29], v[182:183], v[180:181]
	v_pk_fma_f32 v[30:31], v[30:31], v[182:183], v[180:181]
	v_pk_fma_f32 v[32:33], v[32:33], v[182:183], v[180:181]
	v_pk_fma_f32 v[34:35], v[34:35], v[182:183], v[180:181]
	v_pk_fma_f32 v[36:37], v[36:37], v[182:183], v[180:181]
	v_pk_fma_f32 v[38:39], v[38:39], v[182:183], v[180:181]
	v_pk_mul_f32 v[24:25], v[24:25], v[44:45]
	v_pk_mul_f32 v[26:27], v[26:27], v[46:47]
	v_pk_mul_f32 v[28:29], v[28:29], v[40:41]
	v_pk_mul_f32 v[30:31], v[30:31], v[42:43]
	v_pk_mul_f32 v[32:33], v[32:33], v[20:21]
	v_pk_mul_f32 v[34:35], v[34:35], v[22:23]
	v_pk_mul_f32 v[36:37], v[36:37], v[16:17]
	v_pk_mul_f32 v[38:39], v[38:39], v[18:19]
	v_exp_f32_e32 v24, v24
	v_exp_f32_e32 v25, v25
	v_exp_f32_e32 v26, v26
	v_exp_f32_e32 v27, v27
	v_exp_f32_e32 v28, v28
	v_exp_f32_e32 v29, v29
	v_exp_f32_e32 v30, v30
	v_exp_f32_e32 v31, v31
	v_exp_f32_e32 v32, v32
	v_exp_f32_e32 v33, v33
	v_exp_f32_e32 v34, v34
	v_exp_f32_e32 v35, v35
	v_exp_f32_e32 v36, v36
	v_exp_f32_e32 v37, v37
	v_exp_f32_e32 v38, v38
	v_exp_f32_e32 v39, v39
	v_pk_add_f32 v[24:25], v[24:25], 1.0 op_sel_hi:[1,0]
	v_pk_add_f32 v[26:27], v[26:27], 1.0 op_sel_hi:[1,0]
	v_pk_add_f32 v[28:29], v[28:29], 1.0 op_sel_hi:[1,0]
	v_pk_add_f32 v[30:31], v[30:31], 1.0 op_sel_hi:[1,0]
	v_pk_add_f32 v[32:33], v[32:33], 1.0 op_sel_hi:[1,0]
	v_pk_add_f32 v[34:35], v[34:35], 1.0 op_sel_hi:[1,0]
	v_pk_add_f32 v[36:37], v[36:37], 1.0 op_sel_hi:[1,0]
	v_pk_add_f32 v[38:39], v[38:39], 1.0 op_sel_hi:[1,0]
	v_rcp_f32_e32 v24, v24
	v_rcp_f32_e32 v25, v25
	v_rcp_f32_e32 v26, v26
	v_rcp_f32_e32 v27, v27
	v_rcp_f32_e32 v28, v28
	v_rcp_f32_e32 v29, v29
	v_rcp_f32_e32 v30, v30
	v_rcp_f32_e32 v31, v31
	v_rcp_f32_e32 v32, v32
	v_rcp_f32_e32 v33, v33
	v_rcp_f32_e32 v34, v34
	v_rcp_f32_e32 v35, v35
	v_rcp_f32_e32 v36, v36
	v_rcp_f32_e32 v37, v37
	v_rcp_f32_e32 v38, v38
	v_rcp_f32_e32 v39, v39
	v_pk_mul_f32 v[44:45], v[44:45], v[24:25]
	v_pk_mul_f32 v[46:47], v[46:47], v[26:27]
	v_pk_mul_f32 v[40:41], v[40:41], v[28:29]
	v_pk_mul_f32 v[42:43], v[42:43], v[30:31]
	v_pk_mul_f32 v[20:21], v[20:21], v[32:33]
	v_pk_mul_f32 v[22:23], v[22:23], v[34:35]
	v_pk_mul_f32 v[16:17], v[16:17], v[36:37]
	v_pk_mul_f32 v[18:19], v[18:19], v[38:39]
	v_cvt_pk_bf16_f32 v24, v44, v45
	v_cvt_pk_bf16_f32 v25, v46, v47
	v_cvt_pk_bf16_f32 v26, v40, v41
	v_cvt_pk_bf16_f32 v27, v42, v43
	v_cvt_pk_bf16_f32 v28, v20, v21
	v_cvt_pk_bf16_f32 v29, v22, v23
	v_cvt_pk_bf16_f32 v30, v16, v17
	v_cvt_pk_bf16_f32 v31, v18, v19
	global_store_dwordx4 v[160:161], v[24:27], off
	global_store_dwordx4 v[160:161], v[28:31], off offset:256
	s_and_b64 vcc, exec, s[20:21]
	s_cbranch_vccz .Lio_skip_6
	v_pk_mul_f32 v[32:33], v[44:45], v[44:45]
	v_pk_fma_f32 v[32:33], v[46:47], v[46:47], v[32:33]
	v_pk_fma_f32 v[32:33], v[40:41], v[40:41], v[32:33]
	v_pk_fma_f32 v[32:33], v[42:43], v[42:43], v[32:33]
	v_pk_fma_f32 v[32:33], v[20:21], v[20:21], v[32:33]
	v_pk_fma_f32 v[32:33], v[22:23], v[22:23], v[32:33]
	v_pk_fma_f32 v[32:33], v[16:17], v[16:17], v[32:33]
	v_pk_fma_f32 v[32:33], v[18:19], v[18:19], v[32:33]
	s_nop 0
	v_add_f32_e32 v32, v32, v33
	v_mov_b32_e32 v33, v32
	s_nop 1
	v_permlane16_swap_b32_e32 v32, v33
	v_add_f32_e32 v32, v32, v33
	v_mov_b32_e32 v33, v32
	s_nop 1
	v_permlane32_swap_b32_e32 v32, v33
	s_and_saveexec_b64 vcc, s[6:7]
	v_add_f32_e32 v32, v32, v33
	global_atomic_add_f32 v[156:157], v32, off offset:640
	s_mov_b64 exec, vcc
.Lio_skip_6:
	v_lshl_add_u64 v[160:161], v[160:161], 0, s[2:3]
	s_nop 1
	v_pk_mul_f32 v[24:25], v[12:13], v[12:13]
	v_pk_mul_f32 v[26:27], v[14:15], v[14:15]
	v_pk_mul_f32 v[28:29], v[8:9], v[8:9]
	v_pk_mul_f32 v[30:31], v[10:11], v[10:11]
	v_pk_mul_f32 v[32:33], v[4:5], v[4:5]
	v_pk_mul_f32 v[34:35], v[6:7], v[6:7]
	v_pk_mul_f32 v[36:37], v[0:1], v[0:1]
	v_pk_mul_f32 v[38:39], v[2:3], v[2:3]
	v_pk_fma_f32 v[24:25], v[24:25], v[182:183], v[180:181]
	v_pk_fma_f32 v[26:27], v[26:27], v[182:183], v[180:181]
	v_pk_fma_f32 v[28:29], v[28:29], v[182:183], v[180:181]
	v_pk_fma_f32 v[30:31], v[30:31], v[182:183], v[180:181]
	v_pk_fma_f32 v[32:33], v[32:33], v[182:183], v[180:181]
	v_pk_fma_f32 v[34:35], v[34:35], v[182:183], v[180:181]
	v_pk_fma_f32 v[36:37], v[36:37], v[182:183], v[180:181]
	v_pk_fma_f32 v[38:39], v[38:39], v[182:183], v[180:181]
	v_pk_mul_f32 v[24:25], v[24:25], v[12:13]
	v_pk_mul_f32 v[26:27], v[26:27], v[14:15]
	v_pk_mul_f32 v[28:29], v[28:29], v[8:9]
	v_pk_mul_f32 v[30:31], v[30:31], v[10:11]
	v_pk_mul_f32 v[32:33], v[32:33], v[4:5]
	v_pk_mul_f32 v[34:35], v[34:35], v[6:7]
	v_pk_mul_f32 v[36:37], v[36:37], v[0:1]
	v_pk_mul_f32 v[38:39], v[38:39], v[2:3]
	v_exp_f32_e32 v24, v24
	v_exp_f32_e32 v25, v25
	v_exp_f32_e32 v26, v26
	v_exp_f32_e32 v27, v27
	v_exp_f32_e32 v28, v28
	v_exp_f32_e32 v29, v29
	v_exp_f32_e32 v30, v30
	v_exp_f32_e32 v31, v31
	v_exp_f32_e32 v32, v32
	v_exp_f32_e32 v33, v33
	v_exp_f32_e32 v34, v34
	v_exp_f32_e32 v35, v35
	v_exp_f32_e32 v36, v36
	v_exp_f32_e32 v37, v37
	v_exp_f32_e32 v38, v38
	v_exp_f32_e32 v39, v39
	v_pk_add_f32 v[24:25], v[24:25], 1.0 op_sel_hi:[1,0]
	v_pk_add_f32 v[26:27], v[26:27], 1.0 op_sel_hi:[1,0]
	v_pk_add_f32 v[28:29], v[28:29], 1.0 op_sel_hi:[1,0]
	v_pk_add_f32 v[30:31], v[30:31], 1.0 op_sel_hi:[1,0]
	v_pk_add_f32 v[32:33], v[32:33], 1.0 op_sel_hi:[1,0]
	v_pk_add_f32 v[34:35], v[34:35], 1.0 op_sel_hi:[1,0]
	v_pk_add_f32 v[36:37], v[36:37], 1.0 op_sel_hi:[1,0]
	v_pk_add_f32 v[38:39], v[38:39], 1.0 op_sel_hi:[1,0]
	v_rcp_f32_e32 v24, v24
	v_rcp_f32_e32 v25, v25
	v_rcp_f32_e32 v26, v26
	v_rcp_f32_e32 v27, v27
	v_rcp_f32_e32 v28, v28
	v_rcp_f32_e32 v29, v29
	v_rcp_f32_e32 v30, v30
	v_rcp_f32_e32 v31, v31
	v_rcp_f32_e32 v32, v32
	v_rcp_f32_e32 v33, v33
	v_rcp_f32_e32 v34, v34
	v_rcp_f32_e32 v35, v35
	v_rcp_f32_e32 v36, v36
	v_rcp_f32_e32 v37, v37
	v_rcp_f32_e32 v38, v38
	v_rcp_f32_e32 v39, v39
	v_pk_mul_f32 v[12:13], v[12:13], v[24:25]
	v_pk_mul_f32 v[14:15], v[14:15], v[26:27]
	v_pk_mul_f32 v[8:9], v[8:9], v[28:29]
	v_pk_mul_f32 v[10:11], v[10:11], v[30:31]
	v_pk_mul_f32 v[4:5], v[4:5], v[32:33]
	v_pk_mul_f32 v[6:7], v[6:7], v[34:35]
	v_pk_mul_f32 v[0:1], v[0:1], v[36:37]
	v_pk_mul_f32 v[2:3], v[2:3], v[38:39]
	v_cvt_pk_bf16_f32 v24, v12, v13
	v_cvt_pk_bf16_f32 v25, v14, v15
	v_cvt_pk_bf16_f32 v26, v8, v9
	v_cvt_pk_bf16_f32 v27, v10, v11
	v_cvt_pk_bf16_f32 v28, v4, v5
	v_cvt_pk_bf16_f32 v29, v6, v7
	v_cvt_pk_bf16_f32 v30, v0, v1
	v_cvt_pk_bf16_f32 v31, v2, v3
	global_store_dwordx4 v[160:161], v[24:27], off
	global_store_dwordx4 v[160:161], v[28:31], off offset:256
	s_and_b64 vcc, exec, s[20:21]
	s_cbranch_vccz .Lio_skip_7
	v_pk_mul_f32 v[32:33], v[12:13], v[12:13]
	v_pk_fma_f32 v[32:33], v[14:15], v[14:15], v[32:33]
	v_pk_fma_f32 v[32:33], v[8:9], v[8:9], v[32:33]
	v_pk_fma_f32 v[32:33], v[10:11], v[10:11], v[32:33]
	v_pk_fma_f32 v[32:33], v[4:5], v[4:5], v[32:33]
	v_pk_fma_f32 v[32:33], v[6:7], v[6:7], v[32:33]
	v_pk_fma_f32 v[32:33], v[0:1], v[0:1], v[32:33]
	v_pk_fma_f32 v[32:33], v[2:3], v[2:3], v[32:33]
	s_nop 0
	v_add_f32_e32 v32, v32, v33
	v_mov_b32_e32 v33, v32
	s_nop 1
	v_permlane16_swap_b32_e32 v32, v33
	v_add_f32_e32 v32, v32, v33
	v_mov_b32_e32 v33, v32
	s_nop 1
	v_permlane32_swap_b32_e32 v32, v33
	s_and_saveexec_b64 vcc, s[6:7]
	v_add_f32_e32 v32, v32, v33
	global_atomic_add_f32 v[156:157], v32, off offset:704
	s_mov_b64 exec, vcc
.Lio_skip_7:
	s_branch .LBB0_119
.LBB0_155:
	s_waitcnt vmcnt(0)
	s_cmpk_gt_u32 s29, 0xff
	s_mov_b32 s48, 0x5040100
	s_cbranch_scc1 .LBB0_157
	s_barrier
